# attention: running max folded into the QK accumulator init (C=-m) on non-refresh tiles, V fragments 4-7 reuse consumed K-fragment registers
# speedup vs baseline: 1.0143x; 1.0143x over previous
.LBB0_175:
	s_bitcmp1_b32 s7, 0
	s_cselect_b32 s2, 0x5800, 0
	s_add_i32 s10, s2, 0
	v_add3_u32 v104, s10, v110, v142
	v_add3_u32 v147, s10, v138, v143
	ds_read_b128 v[162:165], v104
	ds_read_b128 v[166:169], v104 offset:64
	ds_read_b128 v[170:173], v104 offset:128
	ds_read_b128 v[174:177], v104 offset:3328
	ds_read_b128 v[178:181], v104 offset:3392
	ds_read_b128 v[182:185], v104 offset:3456
	ds_read_b128 v[186:189], v104 offset:6656
	ds_read_b128 v[214:217], v104 offset:6720
	ds_read_b128 v[218:221], v104 offset:6784
	ds_read_b128 v[222:225], v104 offset:9984
	ds_read_b128 v[226:229], v104 offset:10048
	ds_read_b128 v[230:233], v104 offset:10112
	global_load_dwordx4 v[72:75], v[136:137], off
	global_load_dwordx4 v[68:71], v[134:135], off
	global_load_dwordx4 v[64:67], v[132:133], off
	s_and_b32 s21, s7, 15
	s_cbranch_scc0 .Lattn_refresh
	s_waitcnt lgkmcnt(11)
	v_mfma_f32_16x16x32_bf16 v[92:95], v[162:165], v[0:3], v[148:151]
	v_mfma_f32_16x16x32_bf16 v[76:79], v[162:165], v[8:11], v[152:155]
	ds_read_b64 v[234:235], v147 offset:13312
	ds_read_b64 v[236:237], v147 offset:13344
	s_waitcnt lgkmcnt(12)
	v_mfma_f32_16x16x32_bf16 v[92:95], v[166:169], v[4:7], v[92:95]
	v_mfma_f32_16x16x32_bf16 v[76:79], v[166:169], v[12:15], v[76:79]
	ds_read_b64 v[238:239], v147 offset:13376
	ds_read_b64 v[240:241], v147 offset:13408
	s_waitcnt lgkmcnt(13)
	v_mfma_f32_16x16x32_bf16 v[92:95], v[170:173], v[16:19], v[92:95]
	v_mfma_f32_16x16x32_bf16 v[76:79], v[170:173], v[20:23], v[76:79]
	ds_read_b64 v[242:243], v147 offset:15616
	ds_read_b64 v[244:245], v147 offset:15648
	s_waitcnt lgkmcnt(14)
	v_mfma_f32_16x16x32_bf16 v[96:99], v[174:177], v[0:3], v[148:151]
	v_mfma_f32_16x16x32_bf16 v[80:83], v[174:177], v[8:11], v[152:155]
	ds_read_b64 v[246:247], v147 offset:15680
	s_waitcnt lgkmcnt(14)
	v_mfma_f32_16x16x32_bf16 v[96:99], v[178:181], v[4:7], v[96:99]
	v_mfma_f32_16x16x32_bf16 v[80:83], v[178:181], v[12:15], v[80:83]
	ds_read_b64 v[248:249], v147 offset:15712
	s_waitcnt lgkmcnt(14)
	v_mfma_f32_16x16x32_bf16 v[96:99], v[182:185], v[16:19], v[96:99]
	v_mfma_f32_16x16x32_bf16 v[80:83], v[182:185], v[20:23], v[80:83]
	ds_read_b64 v[162:163], v147 offset:17920
	s_waitcnt lgkmcnt(14)
	v_mfma_f32_16x16x32_bf16 v[100:103], v[186:189], v[0:3], v[148:151]
	v_mfma_f32_16x16x32_bf16 v[84:87], v[186:189], v[8:11], v[152:155]
	ds_read_b64 v[164:165], v147 offset:17952
	s_waitcnt lgkmcnt(14)
	v_mfma_f32_16x16x32_bf16 v[100:103], v[214:217], v[4:7], v[100:103]
	v_mfma_f32_16x16x32_bf16 v[84:87], v[214:217], v[12:15], v[84:87]
	ds_read_b64 v[166:167], v147 offset:17984
	s_waitcnt lgkmcnt(14)
	v_mfma_f32_16x16x32_bf16 v[100:103], v[218:221], v[16:19], v[100:103]
	v_mfma_f32_16x16x32_bf16 v[84:87], v[218:221], v[20:23], v[84:87]
	ds_read_b64 v[168:169], v147 offset:18016
	s_waitcnt lgkmcnt(14)
	v_mfma_f32_16x16x32_bf16 v[104:107], v[222:225], v[0:3], v[148:151]
	v_mfma_f32_16x16x32_bf16 v[88:91], v[222:225], v[8:11], v[152:155]
	ds_read_b64 v[170:171], v147 offset:20224
	s_waitcnt lgkmcnt(14)
	v_mfma_f32_16x16x32_bf16 v[104:107], v[226:229], v[4:7], v[104:107]
	v_mfma_f32_16x16x32_bf16 v[88:91], v[226:229], v[12:15], v[88:91]
	ds_read_b64 v[172:173], v147 offset:20256
	s_waitcnt lgkmcnt(14)
	v_mfma_f32_16x16x32_bf16 v[104:107], v[230:233], v[16:19], v[104:107]
	v_mfma_f32_16x16x32_bf16 v[88:91], v[230:233], v[20:23], v[88:91]
	s_waitcnt lgkmcnt(13)
	ds_read_b64 v[174:175], v147 offset:20288
	ds_read_b64 v[176:177], v147 offset:20320
.Lattn_sm:
	v_exp_f32_e32 v92, v92
	v_exp_f32_e32 v93, v93
	v_exp_f32_e32 v94, v94
	v_exp_f32_e32 v95, v95
	v_exp_f32_e32 v96, v96
	v_exp_f32_e32 v97, v97
	v_exp_f32_e32 v98, v98
	v_exp_f32_e32 v99, v99
	v_exp_f32_e32 v100, v100
	v_exp_f32_e32 v101, v101
	v_exp_f32_e32 v102, v102
	v_exp_f32_e32 v103, v103
	v_exp_f32_e32 v104, v104
	v_exp_f32_e32 v105, v105
	v_exp_f32_e32 v106, v106
	v_exp_f32_e32 v107, v107
	v_cvt_pk_bf16_f32 v92, v92, v93
	v_cvt_pk_bf16_f32 v93, v94, v95
	v_cvt_pk_bf16_f32 v94, v96, v97
	v_cvt_pk_bf16_f32 v95, v98, v99
	v_cvt_pk_bf16_f32 v96, v100, v101
	v_cvt_pk_bf16_f32 v97, v102, v103
	v_cvt_pk_bf16_f32 v98, v104, v105
	v_cvt_pk_bf16_f32 v99, v106, v107
	v_mov_b32_e32 v100, s52
	v_mov_b32_e32 v101, s52
	v_mov_b32_e32 v102, s52
	v_mov_b32_e32 v103, s52
	v_exp_f32_e32 v76, v76
	v_exp_f32_e32 v77, v77
	v_exp_f32_e32 v78, v78
	v_exp_f32_e32 v79, v79
	v_exp_f32_e32 v80, v80
	v_exp_f32_e32 v81, v81
	v_exp_f32_e32 v82, v82
	v_exp_f32_e32 v83, v83
	v_exp_f32_e32 v84, v84
	v_exp_f32_e32 v85, v85
	v_exp_f32_e32 v86, v86
	v_exp_f32_e32 v87, v87
	v_exp_f32_e32 v88, v88
	v_exp_f32_e32 v89, v89
	v_exp_f32_e32 v90, v90
	v_exp_f32_e32 v91, v91
	v_cvt_pk_bf16_f32 v76, v76, v77
	v_cvt_pk_bf16_f32 v77, v78, v79
	v_cvt_pk_bf16_f32 v78, v80, v81
	v_cvt_pk_bf16_f32 v79, v82, v83
	v_cvt_pk_bf16_f32 v80, v84, v85
	v_cvt_pk_bf16_f32 v81, v86, v87
	v_cvt_pk_bf16_f32 v82, v88, v89
	v_cvt_pk_bf16_f32 v83, v90, v91
	s_add_i32 s7, s7, 1
	s_bitcmp1_b32 s7, 0
	s_cselect_b32 s2, 0x5800, 0
	s_add_i32 s10, s2, 0
	v_add_u32_e32 v127, s10, v139
	v_add_u32_e32 v129, s10, v140
	v_add_u32_e32 v131, s10, v116
	s_waitcnt vmcnt(2)
	ds_write_b128 v127, v[72:75]
	s_waitcnt vmcnt(0)
	ds_write_b128 v131, v[64:67] offset:13312
	s_and_b64 vcc, exec, s[42:43]
	s_cbranch_vccz .Lattn_skipw
	ds_write_b128 v129, v[68:71]
.Lattn_skipw:
	s_waitcnt lgkmcnt(15)
	v_mfma_f32_16x16x32_bf16 v[60:63], v[234:237], v[92:95], v[60:63]
	v_mfma_f32_16x16x32_bf16 v[56:59], v[234:237], v[76:79], v[56:59]
	s_waitcnt lgkmcnt(14)
	v_mfma_f32_16x16x32_bf16 v[60:63], v[238:241], v[96:99], v[60:63]
	v_mfma_f32_16x16x32_bf16 v[56:59], v[238:241], v[80:83], v[56:59]
	s_waitcnt lgkmcnt(12)
	v_mfma_f32_16x16x32_bf16 v[52:55], v[242:245], v[92:95], v[52:55]
	v_mfma_f32_16x16x32_bf16 v[48:51], v[242:245], v[76:79], v[48:51]
	s_waitcnt lgkmcnt(10)
	v_mfma_f32_16x16x32_bf16 v[52:55], v[246:249], v[96:99], v[52:55]
	v_mfma_f32_16x16x32_bf16 v[48:51], v[246:249], v[80:83], v[48:51]
	s_waitcnt lgkmcnt(8)
	v_mfma_f32_16x16x32_bf16 v[44:47], v[162:165], v[92:95], v[44:47]
	v_mfma_f32_16x16x32_bf16 v[40:43], v[162:165], v[76:79], v[40:43]
	s_waitcnt lgkmcnt(6)
	v_mfma_f32_16x16x32_bf16 v[44:47], v[166:169], v[96:99], v[44:47]
	v_mfma_f32_16x16x32_bf16 v[40:43], v[166:169], v[80:83], v[40:43]
	s_waitcnt lgkmcnt(4)
	v_mfma_f32_16x16x32_bf16 v[36:39], v[170:173], v[92:95], v[36:39]
	v_mfma_f32_16x16x32_bf16 v[32:35], v[170:173], v[76:79], v[32:35]
	s_waitcnt lgkmcnt(2)
	v_mfma_f32_16x16x32_bf16 v[36:39], v[174:177], v[96:99], v[36:39]
	v_mfma_f32_16x16x32_bf16 v[32:35], v[174:177], v[80:83], v[32:35]
	v_mfma_f32_16x16x32_bf16 v[28:31], v[100:103], v[92:95], v[28:31]
	v_mfma_f32_16x16x32_bf16 v[24:27], v[100:103], v[76:79], v[24:27]
	v_mfma_f32_16x16x32_bf16 v[28:31], v[100:103], v[96:99], v[28:31]
	v_mfma_f32_16x16x32_bf16 v[24:27], v[100:103], v[80:83], v[24:27]
	s_waitcnt lgkmcnt(0)
	s_barrier
	v_lshl_add_u64 v[132:133], v[132:133], 0, s[50:51]
	v_lshl_add_u64 v[134:135], v[134:135], 0, s[4:5]
	v_lshl_add_u64 v[136:137], v[136:137], 0, s[4:5]
	s_cmp_eq_u32 s6, s7
	s_cbranch_scc0 .LBB0_175
	s_branch .LBB0_161
.Lattn_refresh:
	s_waitcnt lgkmcnt(11)
	v_mfma_f32_16x16x32_bf16 v[92:95], v[162:165], v[0:3], 0
	v_mfma_f32_16x16x32_bf16 v[76:79], v[162:165], v[8:11], 0
	ds_read_b64 v[234:235], v147 offset:13312
	ds_read_b64 v[236:237], v147 offset:13344
	s_waitcnt lgkmcnt(12)
	v_mfma_f32_16x16x32_bf16 v[92:95], v[166:169], v[4:7], v[92:95]
	v_mfma_f32_16x16x32_bf16 v[76:79], v[166:169], v[12:15], v[76:79]
	ds_read_b64 v[238:239], v147 offset:13376
	ds_read_b64 v[240:241], v147 offset:13408
	s_waitcnt lgkmcnt(13)
	v_mfma_f32_16x16x32_bf16 v[92:95], v[170:173], v[16:19], v[92:95]
	v_mfma_f32_16x16x32_bf16 v[76:79], v[170:173], v[20:23], v[76:79]
	ds_read_b64 v[242:243], v147 offset:15616
	ds_read_b64 v[244:245], v147 offset:15648
	s_waitcnt lgkmcnt(14)
	v_mfma_f32_16x16x32_bf16 v[96:99], v[174:177], v[0:3], 0
	v_mfma_f32_16x16x32_bf16 v[80:83], v[174:177], v[8:11], 0
	ds_read_b64 v[246:247], v147 offset:15680
	s_waitcnt lgkmcnt(14)
	v_mfma_f32_16x16x32_bf16 v[96:99], v[178:181], v[4:7], v[96:99]
	v_mfma_f32_16x16x32_bf16 v[80:83], v[178:181], v[12:15], v[80:83]
	ds_read_b64 v[248:249], v147 offset:15712
	s_waitcnt lgkmcnt(14)
	v_mfma_f32_16x16x32_bf16 v[96:99], v[182:185], v[16:19], v[96:99]
	v_mfma_f32_16x16x32_bf16 v[80:83], v[182:185], v[20:23], v[80:83]
	ds_read_b64 v[162:163], v147 offset:17920
	s_waitcnt lgkmcnt(14)
	v_mfma_f32_16x16x32_bf16 v[100:103], v[186:189], v[0:3], 0
	v_mfma_f32_16x16x32_bf16 v[84:87], v[186:189], v[8:11], 0
	ds_read_b64 v[164:165], v147 offset:17952
	s_waitcnt lgkmcnt(14)
	v_mfma_f32_16x16x32_bf16 v[100:103], v[214:217], v[4:7], v[100:103]
	v_mfma_f32_16x16x32_bf16 v[84:87], v[214:217], v[12:15], v[84:87]
	ds_read_b64 v[166:167], v147 offset:17984
	s_waitcnt lgkmcnt(14)
	v_mfma_f32_16x16x32_bf16 v[100:103], v[218:221], v[16:19], v[100:103]
	v_mfma_f32_16x16x32_bf16 v[84:87], v[218:221], v[20:23], v[84:87]
	ds_read_b64 v[168:169], v147 offset:18016
	s_waitcnt lgkmcnt(14)
	v_mfma_f32_16x16x32_bf16 v[104:107], v[222:225], v[0:3], 0
	v_mfma_f32_16x16x32_bf16 v[88:91], v[222:225], v[8:11], 0
	ds_read_b64 v[170:171], v147 offset:20224
	s_waitcnt lgkmcnt(14)
	v_mfma_f32_16x16x32_bf16 v[104:107], v[226:229], v[4:7], v[104:107]
	v_mfma_f32_16x16x32_bf16 v[88:91], v[226:229], v[12:15], v[88:91]
	ds_read_b64 v[172:173], v147 offset:20256
	s_waitcnt lgkmcnt(14)
	v_mfma_f32_16x16x32_bf16 v[104:107], v[230:233], v[16:19], v[104:107]
	v_mfma_f32_16x16x32_bf16 v[88:91], v[230:233], v[20:23], v[88:91]
	s_waitcnt lgkmcnt(13)
	ds_read_b64 v[174:175], v147 offset:20288
	ds_read_b64 v[176:177], v147 offset:20320
	s_nop 7
	v_max_f32_e32 v127, v93, v93
	v_max_f32_e32 v129, v92, v92
	v_max_f32_e32 v127, v129, v127
	v_max_f32_e32 v129, v95, v95
	v_max_f32_e32 v131, v94, v94
	v_max_f32_e32 v129, v131, v129
	v_max_f32_e32 v131, v99, v99
	v_max_f32_e32 v147, v98, v98
	v_max_f32_e32 v131, v147, v131
	v_max3_f32 v131, v96, v97, v131
	v_max3_f32 v127, v127, v129, v131
	v_max_f32_e32 v129, v103, v103
	v_max_f32_e32 v131, v102, v102
	v_max_f32_e32 v129, v131, v129
	v_max_f32_e32 v131, v107, v107
	v_max_f32_e32 v147, v106, v106
	v_max_f32_e32 v131, v147, v131
	v_max3_f32 v129, v100, v101, v129
	v_max3_f32 v131, v104, v105, v131
	v_max3_f32 v127, v127, v129, v131
	ds_bpermute_b32 v129, v145, v127
	s_waitcnt lgkmcnt(0)
	v_max_f32_e32 v129, v129, v129
	v_max_f32_e32 v127, v127, v129
	ds_bpermute_b32 v129, v144, v127
	s_waitcnt lgkmcnt(0)
	v_max3_f32 v127, v130, v127, v129
	v_sub_f32_e32 v129, v130, v127
	v_exp_f32_e32 v130, v129
	s_nop 0
	v_pk_mul_f32 v[62:63], v[62:63], v[130:131] op_sel_hi:[1,0]
	v_pk_mul_f32 v[60:61], v[60:61], v[130:131] op_sel_hi:[1,0]
	v_pk_mul_f32 v[54:55], v[54:55], v[130:131] op_sel_hi:[1,0]
	v_pk_mul_f32 v[52:53], v[52:53], v[130:131] op_sel_hi:[1,0]
	v_pk_mul_f32 v[46:47], v[46:47], v[130:131] op_sel_hi:[1,0]
	v_pk_mul_f32 v[44:45], v[44:45], v[130:131] op_sel_hi:[1,0]
	v_pk_mul_f32 v[38:39], v[38:39], v[130:131] op_sel_hi:[1,0]
	v_pk_mul_f32 v[36:37], v[36:37], v[130:131] op_sel_hi:[1,0]
	v_pk_mul_f32 v[30:31], v[30:31], v[130:131] op_sel_hi:[1,0]
	v_pk_mul_f32 v[28:29], v[28:29], v[130:131] op_sel_hi:[1,0]
	v_mov_b32_e32 v130, v127
	v_xor_b32_e32 v148, 0x80000000, v127
	v_xor_b32_e32 v149, 0x80000000, v127
	v_xor_b32_e32 v150, 0x80000000, v127
	v_xor_b32_e32 v151, 0x80000000, v127
	v_max_f32_e32 v127, v77, v77
	v_max_f32_e32 v129, v76, v76
	v_max_f32_e32 v127, v129, v127
	v_max_f32_e32 v129, v79, v79
	v_max_f32_e32 v131, v78, v78
	v_max_f32_e32 v129, v131, v129
	v_max_f32_e32 v131, v83, v83
	v_max_f32_e32 v147, v82, v82
	v_max_f32_e32 v131, v147, v131
	v_max3_f32 v131, v80, v81, v131
	v_max3_f32 v127, v127, v129, v131
	v_max_f32_e32 v129, v87, v87
	v_max_f32_e32 v131, v86, v86
	v_max_f32_e32 v129, v131, v129
	v_max_f32_e32 v131, v91, v91
	v_max_f32_e32 v147, v90, v90
	v_max_f32_e32 v131, v147, v131
	v_max3_f32 v129, v84, v85, v129
	v_max3_f32 v131, v88, v89, v131
	v_max3_f32 v127, v127, v129, v131
	ds_bpermute_b32 v129, v145, v127
	s_waitcnt lgkmcnt(0)
	v_max_f32_e32 v129, v129, v129
	v_max_f32_e32 v127, v127, v129
	ds_bpermute_b32 v129, v144, v127
	s_waitcnt lgkmcnt(0)
	v_max3_f32 v131, v128, v127, v129
	v_sub_f32_e32 v127, v128, v131
	v_exp_f32_e32 v128, v127
	s_nop 0
	v_pk_mul_f32 v[58:59], v[58:59], v[128:129] op_sel_hi:[1,0]
	v_pk_mul_f32 v[56:57], v[56:57], v[128:129] op_sel_hi:[1,0]
	v_pk_mul_f32 v[50:51], v[50:51], v[128:129] op_sel_hi:[1,0]
	v_pk_mul_f32 v[48:49], v[48:49], v[128:129] op_sel_hi:[1,0]
	v_pk_mul_f32 v[42:43], v[42:43], v[128:129] op_sel_hi:[1,0]
	v_pk_mul_f32 v[40:41], v[40:41], v[128:129] op_sel_hi:[1,0]
	v_pk_mul_f32 v[34:35], v[34:35], v[128:129] op_sel_hi:[1,0]
	v_pk_mul_f32 v[32:33], v[32:33], v[128:129] op_sel_hi:[1,0]
	v_pk_mul_f32 v[26:27], v[26:27], v[128:129] op_sel_hi:[1,0]
	v_pk_mul_f32 v[24:25], v[24:25], v[128:129] op_sel_hi:[1,0]
	v_mov_b32_e32 v128, v131
	v_xor_b32_e32 v152, 0x80000000, v131
	v_xor_b32_e32 v153, 0x80000000, v131
	v_xor_b32_e32 v154, 0x80000000, v131
	v_xor_b32_e32 v155, 0x80000000, v131
	v_pk_add_f32 v[92:93], v[92:93], v[130:131] op_sel_hi:[1,0] neg_lo:[0,1] neg_hi:[0,1]
	v_pk_add_f32 v[94:95], v[94:95], v[130:131] op_sel_hi:[1,0] neg_lo:[0,1] neg_hi:[0,1]
	v_pk_add_f32 v[96:97], v[96:97], v[130:131] op_sel_hi:[1,0] neg_lo:[0,1] neg_hi:[0,1]
	v_pk_add_f32 v[98:99], v[98:99], v[130:131] op_sel_hi:[1,0] neg_lo:[0,1] neg_hi:[0,1]
	v_pk_add_f32 v[100:101], v[100:101], v[130:131] op_sel_hi:[1,0] neg_lo:[0,1] neg_hi:[0,1]
	v_pk_add_f32 v[102:103], v[102:103], v[130:131] op_sel_hi:[1,0] neg_lo:[0,1] neg_hi:[0,1]
	v_pk_add_f32 v[104:105], v[104:105], v[130:131] op_sel_hi:[1,0] neg_lo:[0,1] neg_hi:[0,1]
	v_pk_add_f32 v[106:107], v[106:107], v[130:131] op_sel_hi:[1,0] neg_lo:[0,1] neg_hi:[0,1]
	v_pk_add_f32 v[76:77], v[76:77], v[128:129] op_sel_hi:[1,0] neg_lo:[0,1] neg_hi:[0,1]
	v_pk_add_f32 v[78:79], v[78:79], v[128:129] op_sel_hi:[1,0] neg_lo:[0,1] neg_hi:[0,1]
	v_pk_add_f32 v[80:81], v[80:81], v[128:129] op_sel_hi:[1,0] neg_lo:[0,1] neg_hi:[0,1]
	v_pk_add_f32 v[82:83], v[82:83], v[128:129] op_sel_hi:[1,0] neg_lo:[0,1] neg_hi:[0,1]
	v_pk_add_f32 v[84:85], v[84:85], v[128:129] op_sel_hi:[1,0] neg_lo:[0,1] neg_hi:[0,1]
	v_pk_add_f32 v[86:87], v[86:87], v[128:129] op_sel_hi:[1,0] neg_lo:[0,1] neg_hi:[0,1]
	v_pk_add_f32 v[88:89], v[88:89], v[128:129] op_sel_hi:[1,0] neg_lo:[0,1] neg_hi:[0,1]
	v_pk_add_f32 v[90:91], v[90:91], v[128:129] op_sel_hi:[1,0] neg_lo:[0,1] neg_hi:[0,1]
	s_branch .Lattn_sm
